# mix phase: first unit of every non-converting block pre-assigned (no work-queue round trip at phase start); dwordx4 weight-conversion loads; kernarg lines touched at entry
# speedup vs baseline: 1.0098x; 1.0073x over previous
.LBB0_905:
	v_writelane_b32 v241, s44, 47
	s_nop 1
	v_writelane_b32 v241, s45, 48
	s_or_b64 exec, exec, s[0:1]
	v_readlane_b32 s0, v242, 1
	v_readlane_b32 s2, v242, 3
	v_readlane_b32 s3, v242, 4
	s_add_u32 s76, s2, 0x30f4000
	s_addc_u32 s77, s3, 0
	s_add_u32 s4, s2, 0x2ff4000
	v_writelane_b32 v241, s4, 49
	s_addc_u32 s4, s3, 0
	v_writelane_b32 v241, s4, 50
	s_add_u32 s4, s2, 0x3034000
	v_writelane_b32 v241, s4, 51
	s_addc_u32 s4, s3, 0
	v_writelane_b32 v241, s4, 52
	s_add_u32 s4, s2, 0x3074000
	v_writelane_b32 v241, s4, 21
	s_addc_u32 s4, s3, 0
	v_writelane_b32 v241, s4, 22
	s_add_u32 s4, s2, 0x30b4000
	v_writelane_b32 v241, s4, 23
	s_addc_u32 s4, s3, 0
	s_add_u32 s70, s2, 0xddc8100
	s_addc_u32 s71, s3, 0
	v_readlane_b32 s1, v242, 2
	s_add_u32 s33, s0, 0x4800000
	v_writelane_b32 v241, s4, 24
	s_addc_u32 s67, s1, 0
	v_readlane_b32 s0, v242, 60
	v_readlane_b32 s4, v241, 0
	v_readlane_b32 s5, v241, 1
	v_readlane_b32 s6, v241, 2
	v_readlane_b32 s7, v241, 3
	v_readlane_b32 s8, v241, 4
	v_readlane_b32 s9, v241, 5
	v_readlane_b32 s10, v241, 6
	v_readlane_b32 s11, v241, 7
	v_readlane_b32 s12, v241, 8
	v_readlane_b32 s13, v241, 9
	v_readlane_b32 s14, v241, 10
	v_readlane_b32 s15, v241, 11
	v_writelane_b32 v241, s88, 16
	v_mbcnt_lo_u32_b32 v136, -1, 0
	s_cmp_lg_u64 s[12:13], 0
	v_writelane_b32 v241, s89, 17
	v_mbcnt_hi_u32_b32 v139, -1, v136
	v_writelane_b32 v241, s33, 15
	s_cselect_b64 s[72:73], -1, 0
	s_add_i32 s58, 0, 0x12000
	s_waitcnt lgkmcnt(0)
	v_and_b32_e32 v0, 64, v139
	v_writelane_b32 v241, s67, 20
	v_readlane_b32 s99, v242, 0
	s_mov_b32 s100, -1
	s_cmpk_lt_u32 s99, 0x100
	s_cselect_b32 s100, s99, s100
	s_sub_u32 s101, s99, 0x60
	s_cmpk_ge_u32 s99, 0x160
	s_cselect_b32 s100, s101, s100
	v_mov_b32_e32 v144, s100
	s_mov_b32 s45, 0
	v_mov_b32_e32 v89, 0
	s_mov_b32 s59, 0x1c000
	s_movk_i32 s40, 0xfefe
	s_movk_i32 s41, 0x180
	s_movk_i32 s48, 0x580
	s_movk_i32 s49, 0x600
	s_add_i32 s69, 0, 0x6000
	s_add_i32 s96, 0, 0x500
	s_add_i32 s97, 0, 0x6500
	v_mov_b32_e32 v138, s58
	v_xor_b32_e32 v140, 16, v139
	v_add_u32_e32 v141, 64, v0
	v_xor_b32_e32 v142, 32, v139
	v_mov_b32_e32 v143, 0xf149f2ca
	v_writelane_b32 v241, s72, 18
	v_readfirstlane_b32 s99, v137
	s_cmp_lg_u32 s99, 64
	s_cbranch_scc1 .Lxbi3_skip
	buffer_inv sc1
	s_waitcnt vmcnt(0)

.LBB0_913:
	s_or_b64 exec, exec, s[4:5]
	s_waitcnt vmcnt(0)
	v_readfirstlane_b32 s4, v1
	s_nop 1
	v_add_u32_e32 v144, s4, v0
	v_add_u32_e32 v144, 0x1a0, v144

.LBB0_922:
	s_or_b64 exec, exec, s[2:3]
	s_waitcnt vmcnt(0)
	v_readfirstlane_b32 s2, v1
	s_nop 1
	v_add_u32_e32 v144, s2, v0
	v_add_u32_e32 v144, 0x1a0, v144

.LBB0_1903:
	s_or_b64 exec, exec, s[0:1]
	v_readlane_b32 s0, v242, 1
	v_readlane_b32 s2, v242, 3
	v_readlane_b32 s3, v242, 4
	s_add_u32 s48, s2, 0x30f4040
	v_mbcnt_hi_u32_b32 v136, -1, v136
	s_addc_u32 s49, s3, 0
	s_add_i32 s33, 0, 0x12000
	s_waitcnt lgkmcnt(0)
	v_and_b32_e32 v0, 64, v136
	v_readlane_b32 s99, v242, 0
	s_mov_b32 s100, -1
	s_cmpk_lt_u32 s99, 0x100
	s_cselect_b32 s100, s99, s100
	s_sub_u32 s101, s99, 0x60
	s_cmpk_ge_u32 s99, 0x160
	s_cselect_b32 s100, s101, s100
	v_mov_b32_e32 v143, s100
	s_mov_b32 s59, 0
	v_mov_b32_e32 v89, 0
	v_mov_b32_e32 v138, s33
	s_mov_b32 s40, 0x1c000
	s_movk_i32 s41, 0xfefe
	s_movk_i32 s50, 0x180
	s_movk_i32 s51, 0x580
	s_movk_i32 s45, 0x600
	v_xor_b32_e32 v139, 16, v136
	v_add_u32_e32 v140, 64, v0
	v_xor_b32_e32 v141, 32, v136
	v_mov_b32_e32 v142, 0xf149f2ca
	v_readfirstlane_b32 s99, v137
	s_cmp_lg_u32 s99, 64
	s_cbranch_scc1 .Lxbi12_skip
	buffer_inv sc1
	s_waitcnt vmcnt(0)

.LBB0_1911:
	s_or_b64 exec, exec, s[4:5]
	s_waitcnt vmcnt(0)
	v_readfirstlane_b32 s4, v1
	s_nop 1
	v_add_u32_e32 v143, s4, v0
	v_add_u32_e32 v143, 0x1a0, v143

.LBB0_1920:
	s_or_b64 exec, exec, s[2:3]
	s_waitcnt vmcnt(0)
	v_readfirstlane_b32 s2, v1
	s_nop 1
	v_add_u32_e32 v143, s2, v0
	v_add_u32_e32 v143, 0x1a0, v143
